# cooperative grid sync split: arrive at kernel start, wait after phase 0, then ordinary XCD barrier (plus OWN combine batching)
# speedup vs baseline: 1.0184x; 1.0184x over previous
.LBB0_10:
	s_waitcnt vmcnt(0)
	s_barrier
	s_and_saveexec_b64 s[4:5], s[52:53]
	s_cbranch_execz .Lcg_arr_done
	buffer_wbl2 sc1
	s_load_dwordx2 s[8:9], s[80:81], 0x150
	v_mov_b32_e32 v2, 0
	v_mov_b32_e32 v4, 1
	s_waitcnt vmcnt(0) lgkmcnt(0)
	global_load_dword v5, v2, s[8:9] offset:40
	global_atomic_add v4, v2, v4, s[8:9] offset:32 sc0
	s_waitcnt vmcnt(0)
	v_add_u32_e32 v6, -1, v5
	v_and_b32_e32 v7, 0xffff, v4
	v_cmp_eq_u32_e32 vcc, v7, v6
	s_and_saveexec_b64 s[10:11], vcc
	s_cbranch_execz .Lcg_notlast
	v_sub_u32_e32 v5, 0x10000, v5
	global_atomic_add v2, v5, s[8:9] offset:32
.Lcg_notlast:
	s_or_b64 exec, exec, s[10:11]
	s_nop 1
	v_readfirstlane_b32 s100, v4
.Lcg_arr_done:
	s_or_b64 exec, exec, s[4:5]
	s_ashr_i32 s3, s34, 31
	s_lshl_b32 s33, s34, 3
	s_bfe_i32 s54, s34, 0x1a0003
	s_add_i32 s1, s34, -1
	s_cmpk_lg_i32 s34, 0x100
	s_cselect_b64 s[4:5], -1, 0
	s_abs_i32 s2, s34
	v_cvt_f32_u32_e32 v1, s2
	v_lshrrev_b32_e32 v2, 20, v0
	v_lshrrev_b32_e32 v0, 10, v0
	v_writelane_b32 v255, s1, 2
	v_rcp_iflag_f32_e32 v1, v1
	v_or_b32_e32 v0, v0, v2
	s_movk_i32 s1, 0x3ff
	v_and_or_b32 v0, v0, s1, v156
	v_mul_f32_e32 v1, 0x4f7ffffe, v1
	s_load_dword s1, s[80:81], 0x100
	v_cvt_u32_f32_e32 v1, v1
	s_mul_i32 s0, s35, s34
	v_writelane_b32 v255, s4, 3
	s_lshl_b32 s6, s34, 9
	s_waitcnt lgkmcnt(0)
	s_mul_i32 s82, s0, s1
	s_sub_i32 s0, 0, s2
	v_readfirstlane_b32 s1, v1
	s_mul_i32 s0, s0, s1
	v_writelane_b32 v255, s5, 4
	s_mul_hi_u32 s0, s1, s0
	v_writelane_b32 v255, s2, 5
	s_add_i32 s0, s1, s0
	v_writelane_b32 v255, s0, 6
	s_add_i32 s0, 0, 0x11000
	v_writelane_b32 v255, s0, 7
	s_add_i32 s0, 0, 0x21800
	v_writelane_b32 v255, s0, 8
	s_add_i32 s0, 0, 0x22000
	v_writelane_b32 v255, s0, 9
	s_add_i32 s0, 0, 0x22ff0
	v_writelane_b32 v255, s0, 10
	s_add_i32 s0, 0, 0x22ff4
	v_writelane_b32 v255, s0, 11
	v_cmp_eq_u32_e64 s[0:1], 0, v0
	s_ashr_i32 s7, s6, 31
	s_lshl_b32 s46, s34, 5
	v_writelane_b32 v255, s0, 12
	s_ashr_i32 s47, s46, 31
	s_lshl_b64 s[56:57], s[46:47], 12
	v_writelane_b32 v255, s1, 13
	s_mov_b32 s0, s6
	v_writelane_b32 v255, s0, 14
	s_lshl_b64 s[14:15], s[46:47], 6
	s_lshl_b64 s[50:51], s[46:47], 11
	v_writelane_b32 v255, s1, 15
	s_lshl_b64 s[0:1], s[6:7], 3
	v_writelane_b32 v255, s0, 16
	v_mbcnt_lo_u32_b32 v1, -1, 0
	s_movk_i32 s55, 0x100
	v_writelane_b32 v255, s1, 17
	v_writelane_b32 v255, s56, 18
	s_lshl_b32 s84, s54, 7
	s_lshl_b32 s5, s54, 1
	v_writelane_b32 v255, s57, 19
	v_writelane_b32 v255, s14, 20
	s_lshl_b32 s83, s34, 4
	s_lshl_b32 s85, s34, 8
	v_writelane_b32 v255, s15, 21
	v_writelane_b32 v255, s50, 22
	v_mov_b32_e32 v159, 0
	s_movk_i32 s42, 0x2000
	s_movk_i32 s87, 0x4000
	s_brev_b32 s35, 1
	s_movk_i32 s36, 0x7f
	s_mov_b32 s65, 0x7e000
	v_mov_b32_e32 v192, 1
	s_mov_b32 s40, 0x800000
	s_mov_b32 s41, 0x5040100
	v_mov_b32_e32 v193, 0x358637bd
	s_mov_b32 s27, 0x20000
	s_brev_b32 s26, 64
	s_brev_b32 s39, 18
	s_mov_b32 s88, 0xfe5163ab
	s_mov_b32 s89, 0x3c439041
	v_mov_b32_e32 v194, 0x3c0881c4
	v_mov_b32_e32 v195, 0xbab64f3b
	v_mbcnt_hi_u32_b32 v197, -1, v1
	v_mov_b64_e32 v[160:161], 0xff
	v_mov_b64_e32 v[162:163], 0x100
	v_mov_b32_e32 v198, 0x7f800000
	v_not_b32_e32 v199, 63
	v_not_b32_e32 v200, 31
	v_mov_b32_e32 v201, 0x7fc00000
	v_mov_b32_e32 v164, 2.0
	v_mov_b32_e32 v196, 0x17800
	v_mov_b32_e32 v210, 0x17c00
	v_mov_b32_e32 v206, 0x1880000
	v_mov_b32_e32 v207, 0x6280000
	v_mov_b32_e32 v208, 0x4c00000
	v_mov_b32_e32 v209, 0x2380000
	v_mov_b32_e32 v157, 0xb00000
	v_mov_b32_e32 v211, 0x6d80000
	v_mov_b32_e32 v212, 0x5700000
	s_movk_i32 s44, 0xef80
	s_movk_i32 s45, 0x2c00
	s_mov_b32 s86, 0
	s_mov_b32 s49, 0
	s_mov_b64 s[60:61], 0x800
	s_brev_b32 s64, 60
	s_mov_b64 s[70:71], 0x80
	s_brev_b32 s30, 32
	s_mov_b32 s38, 0x5800000
	v_writelane_b32 v255, s51, 23
	s_branch .LBB0_13

.LBB0_1079:
	s_waitcnt vmcnt(0) lgkmcnt(0)
	s_barrier
	s_and_saveexec_b64 s[6:7], s[52:53]
	s_cbranch_execz .Lcg_wait_done
	s_load_dwordx2 s[8:9], s[80:81], 0x150
	s_and_b32 s0, s100, 0xffff0000
	s_waitcnt lgkmcnt(0)
.Lcg_spin:
	global_load_dword v1, v159, s[8:9] offset:32 sc1
	s_waitcnt vmcnt(0)
	v_and_b32_e32 v1, 0xffff0000, v1
	v_cmp_ne_u32_e32 vcc, s0, v1
	s_cbranch_vccnz .Lcg_spun
	s_sleep 1
	s_branch .Lcg_spin
.Lcg_spun:
	buffer_inv sc1
	s_getreg_b32 s0, hwreg(HW_REG_XCC_ID, 0, 4)
	s_lshl_b32 s0, s0, 8
	s_and_b32 s0, s0, 0xf00
	s_add_u32 s10, s90, s0
	s_addc_u32 s11, s91, 0
	v_mov_b32_e32 v1, 1
	v_mov_b32_e32 v0, 0x494b000
	global_atomic_add v0, v1, s[10:11] offset:1024
	s_waitcnt vmcnt(0)
.Lcg_wait_done:
	s_or_b64 exec, exec, s[6:7]
	s_branch .LBB0_1024

	.amdhsa_kernel _Z6mk_fwd6Params
		.amdhsa_group_segment_fixed_size 0
		.amdhsa_private_segment_fixed_size 0
		.amdhsa_kernarg_size 504
		.amdhsa_user_sgpr_count 2
		.amdhsa_user_sgpr_dispatch_ptr 0
		.amdhsa_user_sgpr_queue_ptr 0
		.amdhsa_user_sgpr_kernarg_segment_ptr 1
		.amdhsa_user_sgpr_dispatch_id 0
		.amdhsa_user_sgpr_kernarg_preload_length 0
		.amdhsa_user_sgpr_kernarg_preload_offset 0
		.amdhsa_user_sgpr_private_segment_size 0
		.amdhsa_uses_dynamic_stack 0
		.amdhsa_enable_private_segment 0
		.amdhsa_system_sgpr_workgroup_id_x 1
		.amdhsa_system_sgpr_workgroup_id_y 0
		.amdhsa_system_sgpr_workgroup_id_z 0
		.amdhsa_system_sgpr_workgroup_info 0
		.amdhsa_system_vgpr_workitem_id 2
		.amdhsa_next_free_vgpr 256
		.amdhsa_next_free_sgpr 102
		.amdhsa_accum_offset 256
		.amdhsa_reserve_vcc 1
		.amdhsa_float_round_mode_32 0
		.amdhsa_float_round_mode_16_64 0
		.amdhsa_float_denorm_mode_32 3
		.amdhsa_float_denorm_mode_16_64 3
		.amdhsa_dx10_clamp 1
		.amdhsa_ieee_mode 1
		.amdhsa_fp16_overflow 0
		.amdhsa_tg_split 0
		.amdhsa_exception_fp_ieee_invalid_op 0
		.amdhsa_exception_fp_denorm_src 0
		.amdhsa_exception_fp_ieee_div_zero 0
		.amdhsa_exception_fp_ieee_overflow 0
		.amdhsa_exception_fp_ieee_underflow 0
		.amdhsa_exception_fp_ieee_inexact 0
		.amdhsa_exception_int_div_zero 0
	.end_amdhsa_kernel

amdhsa.kernels:
  - .agpr_count:     0
    .args:
      - .offset:         0
        .size:           248
        .value_kind:     by_value
      - .offset:         248
        .size:           4
        .value_kind:     hidden_block_count_x
      - .offset:         252
        .size:           4
        .value_kind:     hidden_block_count_y
      - .offset:         256
        .size:           4
        .value_kind:     hidden_block_count_z
      - .offset:         260
        .size:           2
        .value_kind:     hidden_group_size_x
      - .offset:         262
        .size:           2
        .value_kind:     hidden_group_size_y
      - .offset:         264
        .size:           2
        .value_kind:     hidden_group_size_z
      - .offset:         266
        .size:           2
        .value_kind:     hidden_remainder_x
      - .offset:         268
        .size:           2
        .value_kind:     hidden_remainder_y
      - .offset:         270
        .size:           2
        .value_kind:     hidden_remainder_z
      - .offset:         288
        .size:           8
        .value_kind:     hidden_global_offset_x
      - .offset:         296
        .size:           8
        .value_kind:     hidden_global_offset_y
      - .offset:         304
        .size:           8
        .value_kind:     hidden_global_offset_z
      - .offset:         312
        .size:           2
        .value_kind:     hidden_grid_dims
      - .offset:         336
        .size:           8
        .value_kind:     hidden_multigrid_sync_arg
      - .offset:         368
        .size:           4
        .value_kind:     hidden_dynamic_lds_size
    .group_segment_fixed_size: 0
    .kernarg_segment_align: 8
    .kernarg_segment_size: 504
    .language:       OpenCL C
    .language_version:
      - 2
      - 0
    .max_flat_workgroup_size: 512
    .name:           _Z6mk_fwd6Params
    .private_segment_fixed_size: 0
    .sgpr_count:     108
    .sgpr_spill_count: 24
    .symbol:         _Z6mk_fwd6Params.kd
    .uniform_work_group_size: 1
    .uses_dynamic_stack: false
    .vgpr_count:     256
    .vgpr_spill_count: 0
    .wavefront_size: 64
